# attention loops: row-sum chains start from the first pair, self-max dropped, byte count kept equal mod 8 at each site (e64 encodings)
# speedup vs baseline: 1.0042x; 1.0015x over previous
; #define MFMA32(a, b, c) __builtin_amdgcn_mfma_f32_32x32x16_bf16((a), (b), (c), 0, 0, 0)
; DI int crow(int reg, int h) { return (reg & 3) + 8 * (reg >> 2) + 4 * h; }
; template <int MODE>
; DI void attn_mfma(const Params& p, int l, int b, int hd, int qb, unsigned char* smem) {
;     ...
; #pragma unroll
;     for (int ks = 0; ks < KS; ++ks) {
;       const int kk = mp * 2 + ks;
;       const int key0 = r, key1 = 32 + r;
;       const int o0 = key0 * 128 + (((2 * kk + h2) ^ ((key0 >> 1) & 7)) << 4), o1 = key1 * 128 + (((2 * kk + h2) ^ ((key1 >> 1) & 7)) << 4);
;       SA0 = MFMA32(*(const bf16x8*)(sK + o0), qf[ks], SA0);
;       SA1 = MFMA32(*(const bf16x8*)(sK + o1), qf[ks], SA1);
;       SB0 = MFMA32(*(const bf16x8*)(sK + 16896 + o0), qf[ks], SB0);
;       SB1 = MFMA32(*(const bf16x8*)(sK + 16896 + o1), qf[ks], SB1);
;     }
; #pragma unroll
;     for (int hf = 0; hf < 2; ++hf) {
;     const unsigned char* sVc = sV + hf * 16896;
;     const int tbcur = tile_base(j + hf);
;     f32x16 S[2];
;     S[0] = hf == 0 ? SA0 : SB0;
;     S[1] = hf == 0 ? SA1 : SB1;
;     if (MODE == 1 && j + hf >= 4) {
;       const int iq = tq - NCTX;
;       const int jb = tbcur - NCTX;
; #pragma unroll
;       for (int mt = 0; mt < 2; ++mt)
; #pragma unroll
;         for (int i = 0; i < 16; ++i) {
;           const int dd = iq - (jb + mt * 32 + crow(i, h2));
;           if (dd > 128 || dd < -128) S[mt][i] = -1e30f;
;         }
;     }
;     float mx = -1e30f;
; #pragma unroll
;     for (int mt = 0; mt < 2; ++mt)
; #pragma unroll
;       for (int i = 0; i < 16; ++i) mx = fmaxf(mx, S[mt][i]);
;     mx = fmaxf(mx, __shfl_xor(mx, 32));
;     const float zmx = mx * cexp;
;     if (__any(zmx > mrun + 8.f)) {
;       const float mnew = fmaxf(mrun, zmx);
;       const float alpha = __builtin_amdgcn_exp2f(mrun - mnew);
;       mrun = mnew;
;       lsum *= alpha;
;       const f32x2 al2 = {alpha, alpha};
; #pragma unroll
;       for (int vt = 0; vt < 2; ++vt)
; #pragma unroll
;         for (int i = 0; i < 8; ++i) {
;           f32x2 o = {O[vt][2 * i], O[vt][2 * i + 1]};
;           o = o * al2;
;           O[vt][2 * i] = o.x; O[vt][2 * i + 1] = o.y;
;         }
;     }
.LBB0_582:
	s_mov_b32 s5, 0xf149f2ca
	s_mov_b32 s8, 0x3e8293ee
	s_waitcnt lgkmcnt(6)
	v_mfma_f32_32x32x16_bf16 v[80:95], v[204:207], v[96:99], 0
	v_mfma_f32_32x32x16_bf16 v[80:95], v[208:211], v[100:103], v[80:95]
	s_waitcnt lgkmcnt(4)
	v_mfma_f32_32x32x16_bf16 v[64:79], v[212:215], v[96:99], 0
	v_mfma_f32_32x32x16_bf16 v[64:79], v[216:219], v[100:103], v[64:79]
	s_waitcnt lgkmcnt(0)
	v_mfma_f32_32x32x16_bf16 v[48:63], v[220:223], v[96:99], 0
	ds_read2_b64 v[204:207], v236 offset1:2
	ds_read2_b64 v[208:211], v237 offset0:32 offset1:34
	ds_read2_b64 v[212:215], v236 offset0:4 offset1:6
	ds_read2_b64 v[216:219], v237 offset0:36 offset1:38
	v_mfma_f32_32x32x16_bf16 v[48:63], v[224:227], v[100:103], v[48:63]
	s_nop 1
	v_max3_f32 v146, v80, s5, v81
	v_max3_f32 v146, v146, v82, v83
	v_max3_f32 v146, v146, v84, v85
	v_max3_f32 v146, v146, v86, v87
	v_max3_f32 v146, v146, v88, v89
	v_max3_f32 v146, v146, v90, v91
	v_max3_f32 v146, v146, v92, v93
	v_max3_f32 v146, v146, v94, v95
	v_mfma_f32_32x32x16_bf16 v[32:47], v[228:231], v[96:99], 0
	v_max3_f32 v146, v146, v64, v65
	v_max3_f32 v146, v146, v66, v67
	v_max3_f32 v146, v146, v68, v69
	v_max3_f32 v146, v146, v70, v71
	v_mfma_f32_32x32x16_bf16 v[32:47], v[232:235], v[100:103], v[32:47]
	v_max3_f32 v146, v146, v72, v73
	v_max3_f32 v146, v146, v74, v75
	v_max3_f32 v146, v146, v76, v77
	v_max3_f32 v146, v146, v78, v79
	v_mov_b32_e32 v147, v146
	s_nop 1
	v_permlane32_swap_b32_e32 v147, v146
	ds_read2_b64 v[220:223], v236 offset0:8 offset1:10
	ds_read2_b64 v[224:227], v237 offset0:40 offset1:42
	ds_read2_b64 v[228:231], v236 offset0:12 offset1:14
	ds_read2_b64 v[232:235], v237 offset0:44 offset1:46
	s_waitcnt lgkmcnt(4)
	v_max_f32_e64 v146, v146, v147
	v_mul_f32_e32 v147, 0x3e8293ee, v146
	v_add_f32_e32 v146, 0x41000000, v140
	v_cmp_gt_f32_e32 vcc, v147, v146
	s_cbranch_vccz .Laa_nra
	v_max_f32_e32 v146, v147, v147
	v_max_f32_e32 v147, v140, v140
	v_max_f32_e32 v147, v147, v146
	v_sub_f32_e32 v140, v140, v147
	v_exp_f32_e32 v140, v140
	v_add_f32_e32 v146, 0x41000000, v147
	v_pk_mul_f32 v[18:19], v[18:19], v[140:141] op_sel_hi:[1,0]
	v_pk_mul_f32 v[20:21], v[20:21], v[140:141] op_sel_hi:[1,0]
	v_pk_mul_f32 v[22:23], v[22:23], v[140:141] op_sel_hi:[1,0]
	v_pk_mul_f32 v[24:25], v[24:25], v[140:141] op_sel_hi:[1,0]
	v_pk_mul_f32 v[26:27], v[26:27], v[140:141] op_sel_hi:[1,0]
	v_pk_mul_f32 v[28:29], v[28:29], v[140:141] op_sel_hi:[1,0]
	v_pk_mul_f32 v[16:17], v[16:17], v[140:141] op_sel_hi:[1,0]
	v_pk_mul_f32 v[30:31], v[30:31], v[140:141] op_sel_hi:[1,0]
	v_pk_mul_f32 v[0:1], v[0:1], v[140:141] op_sel_hi:[1,0]
	v_pk_mul_f32 v[2:3], v[2:3], v[140:141] op_sel_hi:[1,0]
	v_pk_mul_f32 v[4:5], v[4:5], v[140:141] op_sel_hi:[1,0]
	v_pk_mul_f32 v[6:7], v[6:7], v[140:141] op_sel_hi:[1,0]
	v_pk_mul_f32 v[8:9], v[8:9], v[140:141] op_sel_hi:[1,0]
	v_pk_mul_f32 v[10:11], v[10:11], v[140:141] op_sel_hi:[1,0]
	v_pk_mul_f32 v[12:13], v[12:13], v[140:141] op_sel_hi:[1,0]
	v_pk_mul_f32 v[14:15], v[14:15], v[140:141] op_sel_hi:[1,0]
	v_mul_f32_e32 v200, v200, v140
	v_mov_b32_e32 v140, v147
; DI unsigned pk2(float a, float b) { hwf32x2 f = {a, b}; hwbf16x2 r = __builtin_convertvector(f, hwbf16x2); return __builtin_bit_cast(unsigned, r); }
; #define MFMA32(a, b, c) __builtin_amdgcn_mfma_f32_32x32x16_bf16((a), (b), (c), 0, 0, 0)
; template <int MODE>
; DI void attn_mfma(const Params& p, int l, int b, int hd, int qb, unsigned char* smem) {
;     ...
;     float mx = -1e30f;
; #pragma unroll
;     for (int mt = 0; mt < 2; ++mt)
; #pragma unroll
;       for (int i = 0; i < 16; ++i) mx = fmaxf(mx, S[mt][i]);
;     mx = fmaxf(mx, __shfl_xor(mx, 32));
;     const float zmx = mx * cexp;
;     if (__any(zmx > mrun + 8.f)) {
;       const float mnew = fmaxf(mrun, zmx);
;       const float alpha = __builtin_amdgcn_exp2f(mrun - mnew);
;       mrun = mnew;
;       lsum *= alpha;
;       const f32x2 al2 = {alpha, alpha};
; #pragma unroll
;       for (int vt = 0; vt < 2; ++vt)
; #pragma unroll
;         for (int i = 0; i < 8; ++i) {
;           f32x2 o = {O[vt][2 * i], O[vt][2 * i + 1]};
;           o = o * al2;
;           O[vt][2 * i] = o.x; O[vt][2 * i + 1] = o.y;
;         }
;     }
;     const f32x2 c2 = {cexp, cexp}, m2 = {mrun, mrun};
;     f32x2 ps2 = {0.f, 0.f};
;     unsigned pk[2][8];
; #pragma unroll
;     for (int mt = 0; mt < 2; ++mt)
; #pragma unroll
;       for (int i = 0; i < 8; ++i) {
;         f32x2 z = {S[mt][2 * i], S[mt][2 * i + 1]};
;         z = z * c2 - m2;
;         f32x2 pv = {__builtin_amdgcn_exp2f(z.x), __builtin_amdgcn_exp2f(z.y)};
;         ps2 = ps2 + pv;
;         pk[mt][i] = pk2(pv.x, pv.y);
;       }
;     lsum += ps2.x + ps2.y;
; #pragma unroll
;     for (int mt = 0; mt < 2; ++mt)
; #pragma unroll
;       for (int s = 0; s < 2; ++s) {
;         const uint4 pu = make_uint4(pk[mt][4 * s], pk[mt][4 * s + 1], pk[mt][4 * s + 2], pk[mt][4 * s + 3]);
;         const bf16x8 pf = __builtin_bit_cast(bf16x8, pu);
; #pragma unroll
;         for (int vt = 0; vt < 2; ++vt) {
;           const unsigned char* bp = sVc + (vt * 32 + r) * 136 + (mt * 32 + 16 * s + 4 * h2) * 2;
;           const uint2 lo = *(const uint2*)(bp);
;           const uint2 hi = *(const uint2*)(bp + 16);
;           const uint4 u = make_uint4(lo.x, lo.y, hi.x, hi.y);
;           O[vt] = MFMA32(__builtin_bit_cast(bf16x8, u), pf, O[vt]);
;         }
;       }
.Laa_nra:
	v_fma_f32 v80, v80, s8, -v140
	v_fma_f32 v81, v81, s8, -v140
	v_fma_f32 v82, v82, s8, -v140
	v_fma_f32 v83, v83, s8, -v140
	v_fma_f32 v84, v84, s8, -v140
	v_fma_f32 v85, v85, s8, -v140
	v_fma_f32 v86, v86, s8, -v140
	v_fma_f32 v87, v87, s8, -v140
	v_exp_f32_e32 v80, v80
	v_exp_f32_e32 v81, v81
	v_exp_f32_e32 v82, v82
	v_exp_f32_e32 v83, v83
	v_exp_f32_e32 v84, v84
	v_exp_f32_e32 v85, v85
	v_exp_f32_e32 v86, v86
	v_exp_f32_e32 v87, v87
	v_add_f32_e32 v148, v82, v80
	v_add_f32_e32 v149, v83, v81
	v_add_f32_e32 v148, v84, v148
	v_add_f32_e32 v149, v85, v149
	v_add_f32_e32 v148, v86, v148
	v_add_f32_e32 v149, v87, v149
	v_cvt_pk_bf16_f32 v80, v80, v81
	v_cvt_pk_bf16_f32 v81, v82, v83
	v_cvt_pk_bf16_f32 v82, v84, v85
	v_cvt_pk_bf16_f32 v83, v86, v87
	v_fma_f32 v88, v88, s8, -v140
	v_fma_f32 v89, v89, s8, -v140
	v_fma_f32 v90, v90, s8, -v140
	v_mfma_f32_32x32x16_bf16 v[16:31], v[204:207], v[80:83], v[16:31]
	v_fma_f32 v91, v91, s8, -v140
	v_fma_f32 v92, v92, s8, -v140
	v_fma_f32 v93, v93, s8, -v140
	v_fma_f32 v94, v94, s8, -v140
	v_fma_f32 v95, v95, s8, -v140
	v_exp_f32_e32 v88, v88
	v_exp_f32_e32 v89, v89
	v_exp_f32_e32 v90, v90
	v_exp_f32_e32 v91, v91
	v_exp_f32_e32 v92, v92
	v_exp_f32_e32 v93, v93
	v_exp_f32_e32 v94, v94
	v_mfma_f32_32x32x16_bf16 v[0:15], v[208:211], v[80:83], v[0:15]
	v_exp_f32_e32 v95, v95
	v_add_f32_e32 v148, v88, v148
	v_add_f32_e32 v149, v89, v149
	v_add_f32_e32 v148, v90, v148
	v_add_f32_e32 v149, v91, v149
	v_add_f32_e32 v148, v92, v148
	v_add_f32_e32 v149, v93, v149
	v_add_f32_e32 v148, v94, v148
	v_add_f32_e32 v149, v95, v149
	v_cvt_pk_bf16_f32 v88, v88, v89
	v_cvt_pk_bf16_f32 v89, v90, v91
	v_cvt_pk_bf16_f32 v90, v92, v93
	v_cvt_pk_bf16_f32 v91, v94, v95
	v_fma_f32 v64, v64, s8, -v140
	v_fma_f32 v65, v65, s8, -v140
	v_fma_f32 v66, v66, s8, -v140
	v_mfma_f32_32x32x16_bf16 v[16:31], v[212:215], v[88:91], v[16:31]
	v_fma_f32 v67, v67, s8, -v140
	v_fma_f32 v68, v68, s8, -v140
	v_fma_f32 v69, v69, s8, -v140
	v_fma_f32 v70, v70, s8, -v140
	v_fma_f32 v71, v71, s8, -v140
	v_exp_f32_e32 v64, v64
	v_exp_f32_e32 v65, v65
	v_exp_f32_e32 v66, v66
	v_exp_f32_e32 v67, v67
	v_exp_f32_e32 v68, v68
	v_exp_f32_e32 v69, v69
	v_exp_f32_e32 v70, v70
	v_mfma_f32_32x32x16_bf16 v[0:15], v[216:219], v[88:91], v[0:15]
	v_exp_f32_e32 v71, v71
	v_add_f32_e32 v148, v64, v148
	v_add_f32_e32 v149, v65, v149
	v_add_f32_e32 v148, v66, v148
	v_add_f32_e32 v149, v67, v149
	v_add_f32_e32 v148, v68, v148
	v_add_f32_e32 v149, v69, v149
	v_add_f32_e32 v148, v70, v148
	v_add_f32_e32 v149, v71, v149
	v_cvt_pk_bf16_f32 v84, v64, v65
	v_cvt_pk_bf16_f32 v85, v66, v67
	v_cvt_pk_bf16_f32 v86, v68, v69
	v_cvt_pk_bf16_f32 v87, v70, v71
	v_fma_f32 v72, v72, s8, -v140
	v_fma_f32 v73, v73, s8, -v140
	v_fma_f32 v74, v74, s8, -v140
	s_waitcnt lgkmcnt(0)
	v_mfma_f32_32x32x16_bf16 v[16:31], v[220:223], v[84:87], v[16:31]
	v_fma_f32 v75, v75, s8, -v140
	v_fma_f32 v76, v76, s8, -v140
	v_fma_f32 v77, v77, s8, -v140
	v_fma_f32 v78, v78, s8, -v140
	v_fma_f32 v79, v79, s8, -v140
	v_exp_f32_e32 v72, v72
	v_exp_f32_e32 v73, v73
	v_exp_f32_e32 v74, v74
	v_exp_f32_e32 v75, v75
	v_exp_f32_e32 v76, v76
	v_exp_f32_e32 v77, v77
	v_exp_f32_e32 v78, v78
	v_mfma_f32_32x32x16_bf16 v[0:15], v[224:227], v[84:87], v[0:15]
	v_exp_f32_e32 v79, v79
	v_add_f32_e32 v148, v72, v148
	v_add_f32_e32 v149, v73, v149
	v_add_f32_e32 v148, v74, v148
	v_add_f32_e32 v149, v75, v149
	v_add_f32_e32 v148, v76, v148
	v_add_f32_e32 v149, v77, v149
	v_add_f32_e32 v148, v78, v148
	v_add_f32_e32 v149, v79, v149
	v_cvt_pk_bf16_f32 v64, v72, v73
	v_cvt_pk_bf16_f32 v65, v74, v75
	v_cvt_pk_bf16_f32 v66, v76, v77
	v_cvt_pk_bf16_f32 v67, v78, v79
	v_add_f32_e32 v151, v148, v149
	v_add_f32_e32 v152, v200, v151
	v_mfma_f32_32x32x16_bf16 v[16:31], v[228:231], v[64:67], v[16:31]
	v_max3_f32 v150, v48, s5, v49
	v_max3_f32 v150, v150, v50, v51
	v_max3_f32 v150, v150, v52, v53
	v_max3_f32 v150, v150, v54, v55
	v_max3_f32 v150, v150, v56, v57
	v_max3_f32 v150, v150, v58, v59
	v_max3_f32 v150, v150, v60, v61
	v_max3_f32 v150, v150, v62, v63
	v_mfma_f32_32x32x16_bf16 v[0:15], v[232:235], v[64:67], v[0:15]
	v_max3_f32 v150, v150, v32, v33
	v_max3_f32 v150, v150, v34, v35
	v_max3_f32 v150, v150, v36, v37
	v_max3_f32 v150, v150, v38, v39
	v_max3_f32 v150, v150, v40, v41
	v_max3_f32 v150, v150, v42, v43
	v_max3_f32 v150, v150, v44, v45
	v_max3_f32 v150, v150, v46, v47
	v_mov_b32_e32 v151, v150
	s_nop 1
	v_permlane32_swap_b32_e32 v151, v150
	ds_read2_b64 v[204:207], v238 offset0:64 offset1:66
	ds_read2_b64 v[208:211], v239 offset0:96 offset1:98
	ds_read2_b64 v[212:215], v238 offset0:68 offset1:70
	ds_read2_b64 v[216:219], v239 offset0:100 offset1:102
	ds_read2_b64 v[220:223], v238 offset0:72 offset1:74
	ds_read2_b64 v[224:227], v239 offset0:104 offset1:106
	ds_read2_b64 v[228:231], v238 offset0:76 offset1:78
	ds_read2_b64 v[232:235], v239 offset0:108 offset1:110
	s_waitcnt lgkmcnt(8)
	v_max_f32_e64 v150, v150, v151
	v_mul_f32_e32 v150, 0x3e8293ee, v150
	v_cmp_gt_f32_e32 vcc, v150, v146
	s_cbranch_vccz .Laa_nrb
	v_max_f32_e32 v150, v150, v150
	v_max_f32_e32 v151, v140, v140
	v_max_f32_e32 v150, v151, v150
	v_sub_f32_e32 v151, v140, v150
	v_exp_f32_e32 v154, v151
	v_mov_b32_e32 v140, v150
	v_pk_mul_f32 v[16:17], v[16:17], v[154:155] op_sel_hi:[1,0]
	v_pk_mul_f32 v[18:19], v[18:19], v[154:155] op_sel_hi:[1,0]
	v_pk_mul_f32 v[20:21], v[20:21], v[154:155] op_sel_hi:[1,0]
	v_pk_mul_f32 v[22:23], v[22:23], v[154:155] op_sel_hi:[1,0]
	v_pk_mul_f32 v[24:25], v[24:25], v[154:155] op_sel_hi:[1,0]
	v_pk_mul_f32 v[26:27], v[26:27], v[154:155] op_sel_hi:[1,0]
	v_pk_mul_f32 v[28:29], v[28:29], v[154:155] op_sel_hi:[1,0]
	v_pk_mul_f32 v[30:31], v[30:31], v[154:155] op_sel_hi:[1,0]
	v_pk_mul_f32 v[0:1], v[0:1], v[154:155] op_sel_hi:[1,0]
	v_pk_mul_f32 v[2:3], v[2:3], v[154:155] op_sel_hi:[1,0]
	v_pk_mul_f32 v[4:5], v[4:5], v[154:155] op_sel_hi:[1,0]
	v_pk_mul_f32 v[6:7], v[6:7], v[154:155] op_sel_hi:[1,0]
	v_pk_mul_f32 v[8:9], v[8:9], v[154:155] op_sel_hi:[1,0]
	v_pk_mul_f32 v[10:11], v[10:11], v[154:155] op_sel_hi:[1,0]
	v_pk_mul_f32 v[12:13], v[12:13], v[154:155] op_sel_hi:[1,0]
	v_pk_mul_f32 v[14:15], v[14:15], v[154:155] op_sel_hi:[1,0]
	v_mul_f32_e32 v152, v152, v154

; template <int MODE>
; DI void attn_mfma(const Params& p, int l, int b, int hd, int qb, unsigned char* smem) {
;     ...
;     float mx = -1e30f;
; #pragma unroll
;     for (int mt = 0; mt < 2; ++mt)
; #pragma unroll
;       for (int i = 0; i < 16; ++i) mx = fmaxf(mx, S[mt][i]);
;     mx = fmaxf(mx, __shfl_xor(mx, 32));
;     const float zmx = mx * cexp;
;     if (__any(zmx > mrun + 8.f)) {
;       const float mnew = fmaxf(mrun, zmx);
;       const float alpha = __builtin_amdgcn_exp2f(mrun - mnew);
;       mrun = mnew;
;       lsum *= alpha;
;       const f32x2 al2 = {alpha, alpha};
; #pragma unroll
;       for (int vt = 0; vt < 2; ++vt)
; #pragma unroll
;         for (int i = 0; i < 8; ++i) {
;           f32x2 o = {O[vt][2 * i], O[vt][2 * i + 1]};
;           o = o * al2;
;           O[vt][2 * i] = o.x; O[vt][2 * i + 1] = o.y;
;         }
;     }
.Lcc_qkdone:
	ds_read2_b64 v[220:223], v213 offset1:2
	ds_read2_b64 v[224:227], v216 offset0:32 offset1:34
	ds_read2_b64 v[228:231], v213 offset0:4 offset1:6
	ds_read2_b64 v[232:235], v216 offset0:36 offset1:38
	ds_read2_b64 v[236:239], v213 offset0:8 offset1:10
	ds_read2_b64 v[240:243], v216 offset0:40 offset1:42
	ds_read2_b64 v[244:247], v213 offset0:12 offset1:14
	ds_read2_b64 v[248:251], v216 offset0:44 offset1:46
	v_max3_f32 v204, v80, s2, v81
	v_max3_f32 v204, v204, v82, v83
	v_max3_f32 v204, v204, v84, v85
	v_max3_f32 v204, v204, v86, v87
	v_max3_f32 v204, v204, v88, v89
	v_max3_f32 v204, v204, v90, v91
	v_max3_f32 v204, v204, v92, v93
	v_max3_f32 v204, v204, v94, v95
	v_max3_f32 v204, v204, v64, v65
	v_max3_f32 v204, v204, v66, v67
	v_max3_f32 v204, v204, v68, v69
	v_max3_f32 v204, v204, v70, v71
	v_max3_f32 v204, v204, v72, v73
	v_max3_f32 v204, v204, v74, v75
	v_max3_f32 v204, v204, v76, v77
	v_max3_f32 v204, v204, v78, v79
	v_mov_b32_e32 v205, v204
	s_nop 1
	v_permlane32_swap_b32_e32 v205, v204
	s_waitcnt lgkmcnt(0)
	v_max_f32_e64 v204, v204, v205
	v_mul_f32_e32 v204, 0x3e38aa3b, v204
	v_add_f32_e32 v206, 0x41000000, v166
	v_cmp_gt_f32_e32 vcc, v204, v206
	s_cbranch_vccz .Lcc_nra
	v_max_f32_e32 v204, v204, v204
	v_max_f32_e32 v205, v166, v166
	v_max_f32_e32 v204, v205, v204
	v_sub_f32_e32 v166, v166, v204
	v_exp_f32_e32 v166, v166
	s_nop 0
	v_pk_mul_f32 v[18:19], v[18:19], v[166:167] op_sel_hi:[1,0]
	v_pk_mul_f32 v[20:21], v[20:21], v[166:167] op_sel_hi:[1,0]
	v_pk_mul_f32 v[22:23], v[22:23], v[166:167] op_sel_hi:[1,0]
	v_pk_mul_f32 v[24:25], v[24:25], v[166:167] op_sel_hi:[1,0]
	v_pk_mul_f32 v[26:27], v[26:27], v[166:167] op_sel_hi:[1,0]
	v_pk_mul_f32 v[28:29], v[28:29], v[166:167] op_sel_hi:[1,0]
	v_pk_mul_f32 v[16:17], v[16:17], v[166:167] op_sel_hi:[1,0]
	v_pk_mul_f32 v[30:31], v[30:31], v[166:167] op_sel_hi:[1,0]
	v_pk_mul_f32 v[0:1], v[0:1], v[166:167] op_sel_hi:[1,0]
	v_pk_mul_f32 v[2:3], v[2:3], v[166:167] op_sel_hi:[1,0]
	v_pk_mul_f32 v[4:5], v[4:5], v[166:167] op_sel_hi:[1,0]
	v_pk_mul_f32 v[6:7], v[6:7], v[166:167] op_sel_hi:[1,0]
	v_pk_mul_f32 v[8:9], v[8:9], v[166:167] op_sel_hi:[1,0]
	v_pk_mul_f32 v[10:11], v[10:11], v[166:167] op_sel_hi:[1,0]
	v_pk_mul_f32 v[12:13], v[12:13], v[166:167] op_sel_hi:[1,0]
	v_pk_mul_f32 v[14:15], v[14:15], v[166:167] op_sel_hi:[1,0]
	v_mul_f32_e32 v200, v200, v166
	v_mov_b32_e32 v166, v204

; template <int MODE>
; DI void attn_mfma(const Params& p, int l, int b, int hd, int qb, unsigned char* smem) {
;     ...
;     float mx = -1e30f;
; #pragma unroll
;     for (int mt = 0; mt < 2; ++mt)
; #pragma unroll
;       for (int i = 0; i < 16; ++i) mx = fmaxf(mx, S[mt][i]);
;     mx = fmaxf(mx, __shfl_xor(mx, 32));
;     const float zmx = mx * cexp;
;     if (__any(zmx > mrun + 8.f)) {
;       const float mnew = fmaxf(mrun, zmx);
;       const float alpha = __builtin_amdgcn_exp2f(mrun - mnew);
;       mrun = mnew;
;       lsum *= alpha;
;       const f32x2 al2 = {alpha, alpha};
; #pragma unroll
;       for (int vt = 0; vt < 2; ++vt)
; #pragma unroll
;         for (int i = 0; i < 8; ++i) {
;           f32x2 o = {O[vt][2 * i], O[vt][2 * i + 1]};
;           o = o * al2;
;           O[vt][2 * i] = o.x; O[vt][2 * i + 1] = o.y;
;         }
;     }
.Lcc_nomaskB:
	v_max3_f32 v210, v48, s2, v49
	v_max3_f32 v210, v210, v50, v51
	v_max3_f32 v210, v210, v52, v53
	v_max3_f32 v210, v210, v54, v55
	v_max3_f32 v210, v210, v56, v57
	v_max3_f32 v210, v210, v58, v59
	v_max3_f32 v210, v210, v60, v61
	v_max3_f32 v210, v210, v62, v63
	v_mfma_f32_32x32x16_bf16 v[0:15], v[248:251], v[64:67], v[0:15]
	v_max3_f32 v210, v210, v32, v33
	v_max3_f32 v210, v210, v34, v35
	v_max3_f32 v210, v210, v36, v37
	v_max3_f32 v210, v210, v38, v39
	v_max3_f32 v210, v210, v40, v41
	v_max3_f32 v210, v210, v42, v43
	v_max3_f32 v210, v210, v44, v45
	v_max3_f32 v210, v210, v46, v47
	v_mov_b32_e32 v211, v210
	s_nop 1
	v_permlane32_swap_b32_e32 v211, v210
	ds_read2_b64 v[220:223], v217 offset0:64 offset1:66
	ds_read2_b64 v[224:227], v218 offset0:96 offset1:98
	ds_read2_b64 v[228:231], v217 offset0:68 offset1:70
	ds_read2_b64 v[232:235], v218 offset0:100 offset1:102
	ds_read2_b64 v[236:239], v217 offset0:72 offset1:74
	ds_read2_b64 v[240:243], v218 offset0:104 offset1:106
	ds_read2_b64 v[244:247], v217 offset0:76 offset1:78
	ds_read2_b64 v[248:251], v218 offset0:108 offset1:110
	s_waitcnt lgkmcnt(8)
	v_max_f32_e64 v210, v210, v211
	v_mul_f32_e32 v210, 0x3e38aa3b, v210
	v_add_f32_e32 v211, 0x41000000, v166
	v_cmp_gt_f32_e32 vcc, v210, v211
	s_cbranch_vccz .Lcc_nrb
	v_max_f32_e32 v210, v210, v210
	v_max_f32_e32 v211, v166, v166
	v_max_f32_e32 v210, v211, v210
	v_sub_f32_e32 v211, v166, v210
	v_exp_f32_e32 v214, v211
	v_mov_b32_e32 v166, v210
	v_pk_mul_f32 v[16:17], v[16:17], v[214:215] op_sel_hi:[1,0]
	v_pk_mul_f32 v[18:19], v[18:19], v[214:215] op_sel_hi:[1,0]
	v_pk_mul_f32 v[20:21], v[20:21], v[214:215] op_sel_hi:[1,0]
	v_pk_mul_f32 v[22:23], v[22:23], v[214:215] op_sel_hi:[1,0]
	v_pk_mul_f32 v[24:25], v[24:25], v[214:215] op_sel_hi:[1,0]
	v_pk_mul_f32 v[26:27], v[26:27], v[214:215] op_sel_hi:[1,0]
	v_pk_mul_f32 v[28:29], v[28:29], v[214:215] op_sel_hi:[1,0]
	v_pk_mul_f32 v[30:31], v[30:31], v[214:215] op_sel_hi:[1,0]
	v_pk_mul_f32 v[0:1], v[0:1], v[214:215] op_sel_hi:[1,0]
	v_pk_mul_f32 v[2:3], v[2:3], v[214:215] op_sel_hi:[1,0]
	v_pk_mul_f32 v[4:5], v[4:5], v[214:215] op_sel_hi:[1,0]
	v_pk_mul_f32 v[6:7], v[6:7], v[214:215] op_sel_hi:[1,0]
	v_pk_mul_f32 v[8:9], v[8:9], v[214:215] op_sel_hi:[1,0]
	v_pk_mul_f32 v[10:11], v[10:11], v[214:215] op_sel_hi:[1,0]
	v_pk_mul_f32 v[12:13], v[12:13], v[214:215] op_sel_hi:[1,0]
	v_pk_mul_f32 v[14:15], v[14:15], v[214:215] op_sel_hi:[1,0]
	v_mul_f32_e32 v212, v212, v214
